# attention: continuation units re-use the 128 overlapping keys from LDS instead of reloading (on top of P0 rebalance + parallel scan)
# baseline (speedup 1.0000x reference)
; __device__ __forceinline__ void attn_phase(const bf16_t* qkv, bf16_t* opart, float* ml, LAS unsigned char* lds, int wave, int lane, int G) {
;     ...
;     const int bx = blockIdx.x, vcu = (G % 8 == 0) ? (bx % 8) * (G / 8) + bx / 8 : bx;
;     const int per = (AT_NWU + G - 1) / G;
;     const int u0 = vcu * per, u1 = (u0 + per < AT_NWU) ? u0 + per : AT_NWU;
;     if (u0 >= u1) return;
;     const int skey = tid >> 3, sc = tid & 7;
;     const unsigned kwoff = (unsigned)(skey * AT_KP + sc * 16), vwoff = (unsigned)(AT_VOFF + (sc >> 2) * 24576 + skey * 64 + (sc & 3) * 16);
;     const unsigned krd = (unsigned)((32 * wave + i32) * AT_KP + hh * 16);
;     const unsigned vrd = (unsigned)(AT_VOFF + (32 * wave + 4 * hh + q4) * 64 + (16 * (p4 & 1) + 8 * (g4 & 1) + 4 * (p4 >> 1)) * 2);
;     u32x4 kreg[6], vreg[6]; bf16x8 qn[4];
;     AttnUnitW cu = attn_decode(u0);
;     ...
;     AT_ISSUE(cu);
.LBB0_694:
	s_abs_i32 s0, s94
	v_cvt_f32_u32_e32 v0, s0
	s_sub_i32 s5, 0, s0
	s_add_i32 s1, s94, 0x17ff
	s_xor_b32 s4, s1, s94
	v_rcp_iflag_f32_e32 v0, v0
	s_abs_i32 s1, s1
	s_ashr_i32 s4, s4, 31
	v_lshrrev_b32_e32 v207, 2, v228
	v_mul_f32_e32 v0, 0x4f7ffffe, v0
	v_cvt_u32_f32_e32 v0, v0
	s_nop 0
	v_readfirstlane_b32 s6, v0
	s_mul_i32 s5, s5, s6
	s_mul_hi_u32 s5, s6, s5
	s_add_i32 s6, s6, s5
	s_mul_hi_u32 s5, s1, s6
	s_mul_i32 s6, s5, s0
	s_sub_i32 s1, s1, s6
	s_add_i32 s7, s5, 1
	s_sub_i32 s6, s1, s0
	s_cmp_ge_u32 s1, s0
	s_cselect_b32 s5, s7, s5
	s_cselect_b32 s1, s6, s1
	s_add_i32 s6, s5, 1
	s_cmp_ge_u32 s1, s0
	s_cselect_b32 s0, s6, s5
	s_xor_b32 s0, s0, s4
	s_sub_i32 s0, s0, s4
	s_mul_i32 s33, s0, s51
	s_add_i32 s0, s33, s0
	s_min_i32 s97, s0, 0x1800
	s_cmp_ge_i32 s33, s97
	s_cbranch_scc1 .LBB0_705
	s_add_u32 s4, s92, 0x2aa00000
	v_readlane_b32 s0, v251, 0
	s_addc_u32 s5, s93, 0
	s_add_u32 s0, s92, 0x36a00000
	s_addc_u32 s1, s93, 0
	s_lshl_b32 s6, s33, 4
	s_and_b32 s86, s6, 0x6000
	s_lshl_b32 s77, s50, 5
	s_and_b32 s8, s33, 0x7ff
	s_lshl_b32 s6, s86, 11
	s_add_u32 s6, s80, s6
	s_addc_u32 s7, s81, 0
	s_bfe_u32 s22, s33, 0x40005
	s_lshl_b32 s10, s22, 20
	s_add_u32 s6, s6, s10
	s_addc_u32 s7, s7, 0
	s_ashr_i32 s72, s33, 11
	s_lshl_b32 s10, s72, 1
	s_lshr_b32 s11, 32, s10
	s_add_i32 s11, s11, -1
	s_and_b32 s11, s11, s8
	s_lshl_b32 s73, s11, 8
	v_and_b32_e32 v164, 31, v204
	s_add_i32 s11, s73, s77
	v_or_b32_e32 v156, s11, v164
	s_sub_i32 s11, 5, s10
	s_mov_b32 s87, 0
	v_mov_b32_e32 v157, 0
	s_lshr_b32 s8, s8, s11
	s_bfm_b32 s11, s10, 0
	v_lshlrev_b64 v[6:7], s10, v[156:157]
	s_and_b32 s12, s8, s11
	s_mov_b32 s13, s87
	v_lshl_add_u64 v[6:7], v[6:7], 0, s[12:13]
	v_lshrrev_b32_e32 v1, 5, v228
	v_lshlrev_b32_e32 v5, 2, v204
	v_lshlrev_b64 v[6:7], 7, v[6:7]
	v_lshrrev_b32_e32 v12, 3, v204
	v_and_b32_e32 v4, 7, v204
	v_and_b32_e32 v14, 8, v5
	v_lshlrev_b32_e32 v5, 4, v204
	v_lshl_add_u64 v[6:7], s[6:7], 0, v[6:7]
	v_lshlrev_b32_e32 v158, 4, v1
	v_mov_b32_e32 v159, v157
	v_or_b32_e32 v166, 0xffffff80, v12
	v_lshlrev_b32_e32 v0, 3, v4
	v_and_b32_e32 v15, 48, v5
	v_lshlrev_b32_e32 v4, 4, v4
	v_lshl_add_u64 v[6:7], v[6:7], 0, v[158:159]
	v_mov_b32_e32 v5, v157
	global_load_dwordx4 v[144:147], v[6:7], off offset:96
	global_load_dwordx4 v[148:151], v[6:7], off offset:64
	global_load_dwordx4 v[152:155], v[6:7], off offset:32
	global_load_dwordx4 v[48:51], v[6:7], off
	v_lshl_add_u64 v[6:7], s[6:7], 0, v[4:5]
	v_add_u32_e32 v5, s73, v166
	v_add_u32_e32 v156, 0x140, v5
	v_lshlrev_b64 v[8:9], s10, v[156:157]
	v_lshl_add_u64 v[8:9], v[8:9], 0, s[12:13]
	v_lshlrev_b64 v[8:9], 7, v[8:9]
	v_lshl_add_u64 v[8:9], v[6:7], 0, v[8:9]
	s_brev_b32 s23, 16
	v_add_co_u32_e32 v10, vcc, s23, v8
	s_brev_b32 s26, 32
	s_nop 0
	v_addc_co_u32_e32 v11, vcc, 0, v9, vcc
	v_add_co_u32_e32 v8, vcc, s26, v8
	v_add_u32_e32 v156, 0x100, v5
	s_nop 0
	v_addc_co_u32_e32 v9, vcc, 0, v9, vcc
	global_load_dwordx4 v[120:123], v[10:11], off
	global_load_dwordx4 v[124:127], v[8:9], off
	v_lshlrev_b64 v[8:9], s10, v[156:157]
	v_lshl_add_u64 v[8:9], v[8:9], 0, s[12:13]
	v_lshlrev_b64 v[8:9], 7, v[8:9]
	v_lshl_add_u64 v[8:9], v[6:7], 0, v[8:9]
	v_add_co_u32_e32 v10, vcc, s23, v8
	v_add_u32_e32 v156, 0xc0, v5
	s_nop 0
	v_addc_co_u32_e32 v11, vcc, 0, v9, vcc
	v_add_co_u32_e32 v8, vcc, s26, v8
	v_and_b32_e32 v3, 3, v207
	s_nop 0
	v_addc_co_u32_e32 v9, vcc, 0, v9, vcc
	global_load_dwordx4 v[112:115], v[10:11], off
	global_load_dwordx4 v[116:119], v[8:9], off
	v_lshlrev_b64 v[8:9], s10, v[156:157]
	v_lshl_add_u64 v[8:9], v[8:9], 0, s[12:13]
	v_lshlrev_b64 v[8:9], 7, v[8:9]
	v_lshl_add_u64 v[8:9], v[6:7], 0, v[8:9]
	v_add_co_u32_e32 v10, vcc, s23, v8
	v_add_u32_e32 v156, 0x80, v5
	s_nop 0
	v_addc_co_u32_e32 v11, vcc, 0, v9, vcc
	v_add_co_u32_e32 v8, vcc, s26, v8
	v_lshlrev_b32_e32 v13, 2, v1
	s_nop 0
	v_addc_co_u32_e32 v9, vcc, 0, v9, vcc
	global_load_dwordx4 v[104:107], v[10:11], off
	global_load_dwordx4 v[108:111], v[8:9], off
	v_lshlrev_b64 v[8:9], s10, v[156:157]
	v_lshl_add_u64 v[8:9], v[8:9], 0, s[12:13]
	v_lshlrev_b64 v[8:9], 7, v[8:9]
	v_lshl_add_u64 v[8:9], v[6:7], 0, v[8:9]
	v_add_co_u32_e32 v10, vcc, s23, v8
	v_or3_b32 v3, v13, v3, s77
	s_nop 0
	v_addc_co_u32_e32 v11, vcc, 0, v9, vcc
	v_add_co_u32_e32 v8, vcc, s26, v8
	v_lshlrev_b32_e32 v3, 6, v3
	s_nop 0
	v_addc_co_u32_e32 v9, vcc, 0, v9, vcc
	global_load_dwordx4 v[92:95], v[10:11], off
	global_load_dwordx4 v[100:103], v[8:9], off
	v_max_i32_e32 v8, 0xffffffc0, v5
; #define LAS __attribute__((address_space(3)))
; __device__ __forceinline__ void attn_phase(const bf16_t* qkv, bf16_t* opart, float* ml, LAS unsigned char* lds, int wave, int lane, int G) {
;     ...
;     const unsigned kwoff = (unsigned)(skey * AT_KP + sc * 16), vwoff = (unsigned)(AT_VOFF + (sc >> 2) * 24576 + skey * 64 + (sc & 3) * 16);
;     const unsigned krd = (unsigned)((32 * wave + i32) * AT_KP + hh * 16);
;     const unsigned vrd = (unsigned)(AT_VOFF + (32 * wave + 4 * hh + q4) * 64 + (16 * (p4 & 1) + 8 * (g4 & 1) + 4 * (p4 >> 1)) * 2);
;     u32x4 kreg[6], vreg[6]; bf16x8 qn[4];
;     AttnUnitW cu = attn_decode(u0);
;     ...
;     AT_ISSUE(cu);
;     for (int u = u0; u < u1; ++u) {
; #pragma unroll
;         for (int i = 0; i < 6; ++i) { *(LAS u32x4*)(lds + kwoff + i * 64 * AT_KP) = kreg[i]; *(LAS u32x4*)(lds + vwoff + i * 64 * 64) = vreg[i]; }
;         bf16x8 q[4];
; #pragma unroll
;         for (int ks = 0; ks < 4; ++ks) q[ks] = qn[ks];
;     ...
;         for (int v = 0; v < 16; ++v) { const int j = (v & 3) + 8 * (v >> 2) + 4 * hh; if (j < i32) st[0][v] = -1e30f; if (j > i32) st[4][v] = -1e30f; }
;         if (l0 < 128) {
; #pragma unroll
;             for (int kt = 0; kt < 4; ++kt)
; #pragma unroll
;                 for (int v = 0; v < 16; ++v) { const int j = (v & 3) + 8 * (v >> 2) + 4 * hh; if (l0 - 128 + 32 * kt + j < 0) st[kt][v] = -1e30f; }
	v_add_u32_e32 v156, 64, v8
	v_lshlrev_b64 v[8:9], s10, v[156:157]
	v_lshl_add_u64 v[8:9], v[8:9], 0, s[12:13]
	v_lshlrev_b64 v[8:9], 7, v[8:9]
	v_lshl_add_u64 v[8:9], v[6:7], 0, v[8:9]
	v_add_co_u32_e32 v10, vcc, s23, v8
	v_max_i32_e32 v156, 0, v5
	s_nop 0
	v_addc_co_u32_e32 v11, vcc, 0, v9, vcc
	v_add_co_u32_e32 v8, vcc, s26, v8
	v_lshlrev_b32_e32 v5, 5, v204
	s_nop 0
	v_addc_co_u32_e32 v9, vcc, 0, v9, vcc
	global_load_dwordx4 v[96:99], v[10:11], off
	global_load_dwordx4 v[88:91], v[8:9], off
	v_lshlrev_b64 v[8:9], s10, v[156:157]
	v_lshl_add_u64 v[8:9], v[8:9], 0, s[12:13]
	v_lshlrev_b64 v[8:9], 7, v[8:9]
	v_lshl_add_u64 v[6:7], v[6:7], 0, v[8:9]
	v_add_co_u32_e32 v8, vcc, s23, v6
	v_and_b32_e32 v5, 32, v5
	s_nop 0
	v_addc_co_u32_e32 v9, vcc, 0, v7, vcc
	v_add_co_u32_e32 v6, vcc, s26, v6
	v_lshlrev_b32_e32 v2, 3, v1
	s_nop 0
	v_addc_co_u32_e32 v7, vcc, 0, v7, vcc
	global_load_dwordx4 v[84:87], v[8:9], off
	global_load_dwordx4 v[80:83], v[6:7], off
	v_and_b32_e32 v1, 16, v204
	v_add3_u32 v3, 0, v3, v5
	v_writelane_b32 v251, s70, 53
	v_add3_u32 v169, v3, v1, v14
	v_or_b32_e32 v1, 1, v13
	v_writelane_b32 v251, s71, 54
	v_cmp_lt_u32_e64 s[14:15], v1, v164
	v_or_b32_e32 v1, 2, v13
	v_cmp_gt_u32_e64 s[16:17], v1, v164
	v_writelane_b32 v251, s14, 55
	s_movk_i32 s9, 0x6000
	v_bfe_u32 v7, v204, 2, 1
	v_writelane_b32 v251, s15, 56
	v_cmp_lt_u32_e64 s[14:15], v1, v164
	v_or_b32_e32 v1, 3, v13
	v_cmp_gt_u32_e64 s[20:21], v1, v164
	v_writelane_b32 v251, s14, 57
	v_lshlrev_b32_e32 v16, 6, v12
	v_mad_u32_u24 v7, v7, s9, 0
	v_writelane_b32 v251, s15, 58
	v_cmp_lt_u32_e64 s[14:15], v1, v164
	v_or_b32_e32 v1, 8, v13
	v_cmp_gt_u32_e64 s[24:25], v1, v164
	v_writelane_b32 v251, s14, 59
	v_add3_u32 v159, v7, v16, v15
	v_mbcnt_hi_u32_b32 v7, -1, v205
	v_writelane_b32 v251, s15, 60
	v_cmp_lt_u32_e64 s[14:15], v1, v164
	v_or_b32_e32 v1, 9, v13
	v_cmp_gt_u32_e64 s[28:29], v1, v164
	v_writelane_b32 v251, s14, 61
	v_and_b32_e32 v10, 64, v7
	v_or_b32_e32 v165, s77, v164
	v_writelane_b32 v251, s15, 62
	v_cmp_lt_u32_e64 s[14:15], v1, v164
	v_or_b32_e32 v1, 10, v13
	v_cmp_gt_u32_e64 s[34:35], v1, v164
	v_writelane_b32 v251, s14, 63
	s_movk_i32 s6, 0x90
	v_xor_b32_e32 v9, 32, v7
	v_writelane_b32 v250, s15, 0
	v_cmp_lt_u32_e64 s[14:15], v1, v164
	v_or_b32_e32 v1, 11, v13
	v_cmp_gt_u32_e64 s[38:39], v1, v164
	v_writelane_b32 v250, s14, 1
	v_add_u32_e32 v10, 64, v10
	v_mul_lo_u32 v6, v165, s6
	v_writelane_b32 v250, s15, 2
	v_cmp_lt_u32_e64 s[14:15], v1, v164
	v_or_b32_e32 v1, 16, v13
	v_cmp_gt_u32_e64 s[42:43], v1, v164
	v_writelane_b32 v250, s14, 3
	v_cmp_lt_i32_e32 vcc, v9, v10
	s_lshl_b32 s27, 1, s10
	v_writelane_b32 v250, s15, 4
	v_cmp_lt_u32_e64 s[14:15], v1, v164
	v_or_b32_e32 v1, 17, v13
	v_cmp_lt_u32_e64 s[44:45], v1, v164
	v_cmp_gt_u32_e64 s[46:47], v1, v164
	v_or_b32_e32 v1, 18, v13
	v_cmp_lt_u32_e64 s[48:49], v1, v164
	v_cmp_gt_u32_e64 s[50:51], v1, v164
	v_or_b32_e32 v1, 19, v13
	v_cmp_lt_u32_e64 s[52:53], v1, v164
	v_cmp_gt_u32_e64 s[54:55], v1, v164
	v_or_b32_e32 v1, 24, v13
	v_cmp_lt_u32_e64 s[56:57], v1, v164
	v_cmp_gt_u32_e64 s[58:59], v1, v164
	v_or_b32_e32 v1, 25, v13
	v_cmp_lt_u32_e64 s[60:61], v1, v164
	v_cmp_gt_u32_e64 s[62:63], v1, v164
	v_or_b32_e32 v1, 26, v13
	v_mad_u32_u24 v8, v12, s6, 0
	v_add_u32_e32 v6, 0, v6
	v_cndmask_b32_e32 v7, v7, v9, vcc
	v_writelane_b32 v250, s14, 5
	v_cmp_lt_u32_e64 s[64:65], v1, v164
	v_cmp_gt_u32_e64 s[66:67], v1, v164
	v_or_b32_e32 v1, 27, v13
	s_waitcnt vmcnt(15)
	v_mov_b64_e32 v[128:129], v[144:145]
	s_waitcnt vmcnt(14)
	v_mov_b64_e32 v[132:133], v[148:149]
	s_waitcnt vmcnt(13)
	v_mov_b64_e32 v[136:137], v[152:153]
	s_waitcnt vmcnt(12)
	v_mov_b64_e32 v[142:143], v[50:51]
	v_add_u32_e32 v167, 0xd800, v159
	v_lshlrev_b32_e32 v168, 2, v7
	v_add_u32_e32 v170, 0xd800, v169
	v_cmp_gt_u32_e64 s[6:7], 32, v228
	v_cmp_lt_u32_e64 s[8:9], v13, v164
	v_cmp_gt_u32_e64 s[10:11], v13, v164
	v_writelane_b32 v250, s15, 6
	v_cmp_lt_u32_e64 s[68:69], v1, v164
	v_cmp_gt_u32_e64 s[70:71], v1, v164
	v_add_u32_e32 v171, v8, v4
	v_lshlrev_b32_e32 v160, 1, v0
	v_lshlrev_b32_e32 v162, 1, v2
	v_add_u32_e32 v172, v6, v158
	v_mov_b32_e32 v173, 0xf149f2ca
	v_mov_b64_e32 v[130:131], v[146:147]
	v_mov_b64_e32 v[134:135], v[150:151]
	v_mov_b64_e32 v[138:139], v[154:155]
	v_mov_b64_e32 v[140:141], v[48:49]
	s_mov_b32 s30, s27
	s_mov_b32 s31, s22
	s_mov_b32 s36, s73
	s_mov_b32 s76, 0x3e38aa3b
	s_mov_b64 s[14:15], s[86:87]
	s_mov_b64 s[18:19], s[86:87]
	s_mov_b32 s98, 0
	s_branch .LBB0_697

; #define LAS __attribute__((address_space(3)))
; __device__ __forceinline__ void attn_phase(const bf16_t* qkv, bf16_t* opart, float* ml, LAS unsigned char* lds, int wave, int lane, int G) {
;     ...
;     for (int u = u0; u < u1; ++u) {
; #pragma unroll
;         for (int i = 0; i < 6; ++i) { *(LAS u32x4*)(lds + kwoff + i * 64 * AT_KP) = kreg[i]; *(LAS u32x4*)(lds + vwoff + i * 64 * 64) = vreg[i]; }
;         bf16x8 q[4];
; #pragma unroll
;         for (int ks = 0; ks < 4; ++ks) q[ks] = qn[ks];
;         const AttnUnitW t = cu;
;         __syncthreads();
;         if (u + 1 < u1) { cu = attn_decode(u + 1); AT_ISSUE(cu); }
.LBB0_697:
	s_add_i32 s33, s33, 1
	s_cmp_ge_i32 s33, s97
	s_cselect_b64 s[78:79], -1, 0
	s_and_b64 vcc, exec, s[78:79]
	s_mov_b32 s82, s12
	s_mov_b32 s37, s72
	s_waitcnt vmcnt(0)
	s_cmp_eq_u32 s98, 0
	s_cbranch_scc1 .Lattn_nocopy
	ds_read_b128 v[80:83], v171 offset:36864
	ds_read_b128 v[88:91], v171 offset:46080
	ds_read_b128 v[84:87], v167 offset:16384
	ds_read_b128 v[96:99], v167 offset:20480
	s_waitcnt lgkmcnt(0)
.Lattn_nocopy:
	ds_write_b128 v171, v[80:83]
	ds_write_b128 v159, v[84:87] offset:55296
	ds_write_b128 v171, v[88:91] offset:9216
	ds_write_b128 v159, v[96:99] offset:59392
	ds_write_b128 v171, v[100:103] offset:18432
	ds_write_b128 v159, v[92:95] offset:63488
	ds_write_b128 v171, v[108:111] offset:27648
	ds_write_b128 v167, v[104:107] offset:12288
	ds_write_b128 v171, v[116:119] offset:36864
	ds_write_b128 v167, v[112:115] offset:16384
	ds_write_b128 v171, v[124:127] offset:46080
	ds_write_b128 v167, v[120:123] offset:20480
	s_waitcnt lgkmcnt(0)
	s_barrier
	s_cbranch_vccnz .LBB0_699
	s_ashr_i32 s37, s33, 11
	s_lshl_b32 s40, s37, 1
	s_lshr_b32 s18, 32, s40
	s_and_b32 s13, s33, 0x7ff
	s_add_i32 s18, s18, -1
	s_sub_i32 s19, 5, s40
	s_and_b32 s18, s18, s13
	s_lshr_b32 s13, s13, s19
	s_bfm_b32 s19, s40, 0
	s_and_b32 s82, s13, s19
	s_lshl_b32 s13, s33, 4
	s_and_b32 s86, s13, 0x6000
	s_lshl_b32 s30, 1, s40
	s_bfe_u32 s31, s33, 0x40005
	s_lshl_b32 s36, s18, 8
	s_lshl_b32 s13, s86, 11
	s_add_u32 s13, s80, s13
	v_add_u32_e32 v6, s36, v166
	s_addc_u32 s19, s81, 0
	s_lshl_b32 s18, s31, 20
	v_max_i32_e32 v156, 0, v6
	s_add_u32 s18, s13, s18
	s_mov_b32 s83, s87
	v_lshlrev_b64 v[2:3], s40, v[156:157]
	s_addc_u32 s19, s19, 0
	v_mov_b32_e32 v161, v157
	v_lshl_add_u64 v[2:3], v[2:3], 0, s[82:83]
	v_lshl_add_u64 v[0:1], s[18:19], 0, v[160:161]
	v_lshlrev_b64 v[2:3], 7, v[2:3]
	v_lshl_add_u64 v[2:3], v[0:1], 0, v[2:3]
	v_add_co_u32_e32 v4, vcc, s26, v2
	v_mov_b32_e32 v163, v157
	s_nop 0
	v_addc_co_u32_e32 v5, vcc, 0, v3, vcc
	v_add_co_u32_e32 v2, vcc, s23, v2
	s_nop 1
	v_addc_co_u32_e32 v3, vcc, 0, v3, vcc
	s_mov_b32 s98, s36
	s_cmp_lg_u32 s36, 0
	s_cbranch_scc1 .Lattn_skip0
	global_load_dwordx4 v[80:83], v[4:5], off
	global_load_dwordx4 v[84:87], v[2:3], off
.Lattn_skip0:
	v_max_i32_e32 v2, 0xffffffc0, v6
	v_add_u32_e32 v156, 64, v2
	v_lshlrev_b64 v[2:3], s40, v[156:157]
	v_lshl_add_u64 v[2:3], v[2:3], 0, s[82:83]
	v_lshlrev_b64 v[2:3], 7, v[2:3]
	v_lshl_add_u64 v[2:3], v[0:1], 0, v[2:3]
	v_add_co_u32_e32 v4, vcc, s26, v2
	s_nop 1
	v_addc_co_u32_e32 v5, vcc, 0, v3, vcc
	v_add_co_u32_e32 v2, vcc, s23, v2
	s_nop 1
	v_addc_co_u32_e32 v3, vcc, 0, v3, vcc
	s_cmp_lg_u32 s36, 0
	s_cbranch_scc1 .Lattn_skip1
	global_load_dwordx4 v[88:91], v[4:5], off
	global_load_dwordx4 v[96:99], v[2:3], off
.Lattn_skip1:
	v_max_i32_e32 v2, 0xffffff80, v6
	v_add_u32_e32 v156, 0x80, v2
	v_lshlrev_b64 v[2:3], s40, v[156:157]
	v_lshl_add_u64 v[2:3], v[2:3], 0, s[82:83]
	v_lshlrev_b64 v[2:3], 7, v[2:3]
	v_lshl_add_u64 v[2:3], v[0:1], 0, v[2:3]
	v_add_co_u32_e32 v4, vcc, s26, v2
	s_nop 1
	v_addc_co_u32_e32 v5, vcc, 0, v3, vcc
	v_add_co_u32_e32 v2, vcc, s23, v2
	s_nop 1
	v_addc_co_u32_e32 v3, vcc, 0, v3, vcc
	global_load_dwordx4 v[100:103], v[4:5], off
	global_load_dwordx4 v[92:95], v[2:3], off
	v_max_i32_e32 v2, 0xffffff40, v6
	v_add_u32_e32 v156, 0xc0, v2
	v_lshlrev_b64 v[2:3], s40, v[156:157]
	v_lshl_add_u64 v[2:3], v[2:3], 0, s[82:83]
	v_lshlrev_b64 v[2:3], 7, v[2:3]
	v_lshl_add_u64 v[2:3], v[0:1], 0, v[2:3]
	v_add_co_u32_e32 v4, vcc, s26, v2
	s_nop 1
	v_addc_co_u32_e32 v5, vcc, 0, v3, vcc
	v_add_co_u32_e32 v2, vcc, s23, v2
	s_nop 1
	v_addc_co_u32_e32 v3, vcc, 0, v3, vcc
	global_load_dwordx4 v[108:111], v[4:5], off
	global_load_dwordx4 v[104:107], v[2:3], off
	v_max_i32_e32 v2, 0xffffff00, v6
	v_add_u32_e32 v156, 0x100, v2
	v_lshlrev_b64 v[2:3], s40, v[156:157]
	v_lshl_add_u64 v[2:3], v[2:3], 0, s[82:83]
	v_lshlrev_b64 v[2:3], 7, v[2:3]
	v_lshl_add_u64 v[2:3], v[0:1], 0, v[2:3]
	v_add_co_u32_e32 v4, vcc, s26, v2
	s_nop 1
	v_addc_co_u32_e32 v5, vcc, 0, v3, vcc
	v_add_co_u32_e32 v2, vcc, s23, v2
	s_nop 1
	v_addc_co_u32_e32 v3, vcc, 0, v3, vcc
	global_load_dwordx4 v[116:119], v[4:5], off
	global_load_dwordx4 v[112:115], v[2:3], off
	v_max_i32_e32 v2, 0xfffffec0, v6
	v_add_u32_e32 v156, 0x140, v2
	v_lshlrev_b64 v[2:3], s40, v[156:157]
	v_lshl_add_u64 v[2:3], v[2:3], 0, s[82:83]
	v_lshlrev_b64 v[2:3], 7, v[2:3]
	v_lshl_add_u64 v[0:1], v[0:1], 0, v[2:3]
	v_add_co_u32_e32 v2, vcc, s26, v0
	s_nop 1
	v_addc_co_u32_e32 v3, vcc, 0, v1, vcc
	v_add_co_u32_e32 v0, vcc, s23, v0
	s_nop 1
	v_addc_co_u32_e32 v1, vcc, 0, v1, vcc
	global_load_dwordx4 v[124:127], v[2:3], off
	global_load_dwordx4 v[120:123], v[0:1], off
	v_add_u32_e32 v0, s36, v165
	v_ashrrev_i32_e32 v1, 31, v0
	v_lshlrev_b64 v[0:1], s40, v[0:1]
	v_lshl_add_u64 v[0:1], v[0:1], 0, s[82:83]
	v_lshlrev_b64 v[0:1], 7, v[0:1]
	v_lshl_add_u64 v[0:1], s[18:19], 0, v[0:1]
	v_lshl_add_u64 v[0:1], v[0:1], 0, v[162:163]
	global_load_dwordx4 v[140:143], v[0:1], off
	global_load_dwordx4 v[136:139], v[0:1], off offset:32
	global_load_dwordx4 v[132:135], v[0:1], off offset:64
	global_load_dwordx4 v[128:131], v[0:1], off offset:96
	s_mov_b64 s[18:19], s[86:87]
